# weight-conversion tile stride derived from the grid size (no functional change at 256 blocks)
# speedup vs baseline: 1.0063x; 1.0063x over previous
; #define LBAR() do { asm volatile("s_waitcnt lgkmcnt(0)" ::: "memory"); __builtin_amdgcn_s_barrier(); asm volatile("" ::: "memory"); } while (0)
; __device__ __forceinline__ bf16_t f2bf(float f) { return (bf16_t)(cvt_pk_bf16(f, 0.f) & 0xffffu); }
; __device__ __forceinline__ void convert_weights(const int TID, const int BID, const Params& p, int l, LAS float* tile) {
;     ...
;     { const float* src = p.in[4] + (size_t)l * D * NIN; const int tx = TID & 63, ty = TID >> 6; float v[8];
;       { const int t = b < 32 * 169 ? b : 0; const int kt = t / 169, ntl = t - kt * 169; const int ncl = (ntl * 64 + tx < NIN) ? ntl * 64 + tx : NIN - 1;
; #pragma unroll
;         for (int i = 0; i < 8; ++i) v[i] = src[(size_t)(kt * 64 + ty + 8 * i) * NIN + ncl]; }
;       for (int t = b; t < 32 * 169; t += G) { const int kt = t / 169, ntl = t - kt * 169, k0 = kt * 64, n0 = ntl * 64;
; #pragma unroll
;           for (int i = 0; i < 8; ++i) tile[(ty + 8 * i) * 65 + tx] = v[i];
;           { const int tn = (t + G < 32 * 169) ? t + G : t; const int ktn = tn / 169, ntn = tn - ktn * 169; const int ncl = (ntn * 64 + tx < NIN) ? ntn * 64 + tx : NIN - 1;
; #pragma unroll
;             for (int i = 0; i < 8; ++i) v[i] = src[(size_t)(ktn * 64 + ty + 8 * i) * NIN + ncl]; }
;           LBAR();
; #pragma unroll
;           for (int i = 0; i < 8; ++i) { const int nn = ty + 8 * i; int n = n0 + nn;
;               if (n < NIN) { n = (n < 2560) ? n : (n < 2592 ? n + (C_GLR - 2560) : n - 32); btin[(size_t)n * D + k0 + tx] = f2bf(tile[tx * 65 + nn]); } }
;           LBAR(); } }
.Lcw_skip7:
	s_lshl_b32 s8, s96, 3
	s_add_i32 s39, s39, s8
	s_branch .Lcw_loop
